# v126 + final fix-up pass P12: all 32 slice loads in flight and residual load issued early; P7: early full wait removed
# speedup vs baseline: 1.0008x; 1.0008x over previous
; __device__ __forceinline__ float bf_lo(unsigned w) { return __uint_as_float(w << 16); }
; __device__ __forceinline__ float bf_hi(unsigned w) { return __uint_as_float(w & 0xffff0000u); }
; __device__ __forceinline__ void fix_gate(const float* part, int nsl, const bf16_t* z, bf16_t* mixed, int gw, int ngw, int lane) {
;     for (int it = gw; it < NTAIL * 8; it += ngw) {
;         const int rloc = it >> 3, row = TAIL0 + rloc, col = (it & 7) * 256 + lane * 4;
;         const bf16_t* p = (const bf16_t*)part + (size_t)rloc * 2048 + col;
;         f32x4_t a = (f32x4_t){0.f, 0.f, 0.f, 0.f}, b = (f32x4_t){0.f, 0.f, 0.f, 0.f};
; #pragma unroll 8
;         for (int s = 0; s < nsl; ++s) { const u32x2_t wa = __builtin_nontemporal_load((const u32x2_t*)(p + (size_t)s * (256 * 2048))), wb = __builtin_nontemporal_load((const u32x2_t*)(p + (size_t)(s + nsl) * (256 * 2048)));
;             a += (f32x4_t){bf_lo(wa.x), bf_hi(wa.x), bf_lo(wa.y), bf_hi(wa.y)}; b += (f32x4_t){bf_lo(wb.x), bf_hi(wb.x), bf_lo(wb.y), bf_hi(wb.y)}; }
;         const u32x2_t gc = *(const u32x2_t*)(z + (size_t)row * DIN + ZO_GC + col), ga = *(const u32x2_t*)(z + (size_t)row * DIN + ZO_GA + col);
.LBB0_1040:
	s_ashr_i32 s0, s35, 3
	s_and_b32 s1, s2, 0x700
	v_or_b32_e32 v0, s1, v241
	s_ashr_i32 s1, s0, 31
	s_lshl_b64 s[16:17], s[0:1], 12
	s_add_u32 s16, s86, s16
	v_lshlrev_b32_e32 v0, 1, v0
	s_addc_u32 s17, s87, s17
	v_lshl_add_u64 v[2:3], s[16:17], 0, v[0:1]
	s_add_i32 s18, s0, 0x2000
	v_add_co_u32_e64 v8, s[0:1], s13, v2
	global_load_dwordx2 v[4:5], v0, s[16:17] nt
	s_nop 0
	v_addc_co_u32_e64 v9, s[0:1], 0, v3, s[0:1]
	v_add_co_u32_e64 v10, s[0:1], s14, v2
	v_add_co_u32_e32 v6, vcc, s12, v2
	s_nop 0
	v_addc_co_u32_e64 v11, s[0:1], 0, v3, s[0:1]
	v_add_co_u32_e64 v12, s[0:1], s15, v2
	s_ashr_i32 s19, s18, 31
	s_nop 0
	v_addc_co_u32_e64 v13, s[0:1], 0, v3, s[0:1]
	v_add_co_u32_e64 v14, s[0:1], s20, v2
	s_mul_i32 s17, s18, 0x4400
	s_nop 0
	v_addc_co_u32_e64 v15, s[0:1], 0, v3, s[0:1]
	v_add_co_u32_e64 v16, s[0:1], s21, v2
	v_addc_co_u32_e32 v7, vcc, 0, v3, vcc
	s_nop 0
	v_addc_co_u32_e64 v17, s[0:1], 0, v3, s[0:1]
	v_add_co_u32_e64 v18, s[0:1], s22, v2
	s_mul_hi_i32 s16, s18, 0x4400
	s_nop 0
	v_addc_co_u32_e64 v19, s[0:1], 0, v3, s[0:1]
	v_add_co_u32_e64 v20, s[0:1], s23, v2
	v_addc_co_u32_e64 v21, s[0:1], 0, v3, s[0:1]
	v_add_co_u32_e64 v22, s[0:1], s24, v2
	s_nop 0
	v_addc_co_u32_e64 v23, s[0:1], 0, v3, s[0:1]
	v_add_co_u32_e64 v24, s[0:1], s25, v2
	s_nop 0
	v_addc_co_u32_e64 v25, s[0:1], 0, v3, s[0:1]
	v_add_co_u32_e64 v26, s[0:1], s26, v2
	s_nop 0
	v_addc_co_u32_e64 v27, s[0:1], 0, v3, s[0:1]
	v_add_co_u32_e64 v28, s[0:1], s27, v2
	s_nop 0
	v_addc_co_u32_e64 v29, s[0:1], 0, v3, s[0:1]
	v_add_co_u32_e64 v30, s[0:1], s28, v2
	s_nop 0
	v_addc_co_u32_e64 v31, s[0:1], 0, v3, s[0:1]
	v_add_co_u32_e64 v32, s[0:1], s29, v2
	s_nop 1
	v_addc_co_u32_e64 v33, s[0:1], 0, v3, s[0:1]
	v_add_co_u32_e64 v34, s[0:1], s30, v2
	s_nop 1
	v_addc_co_u32_e64 v35, s[0:1], 0, v3, s[0:1]
	s_add_u32 s0, s4, s17
	global_load_dwordx2 v[14:15], v[14:15], off nt
	s_nop 0
	global_load_dwordx2 v[16:17], v[16:17], off nt
	s_nop 0
	global_load_dwordx2 v[18:19], v[18:19], off nt
	s_nop 0
	global_load_dwordx2 v[20:21], v[20:21], off nt
	s_nop 0
	global_load_dwordx2 v[22:23], v[22:23], off nt
	s_nop 0
	global_load_dwordx2 v[24:25], v[24:25], off nt
	s_nop 0
	global_load_dwordx2 v[26:27], v[26:27], off nt
	s_nop 0
	global_load_dwordx2 v[28:29], v[28:29], off nt
	s_nop 0
	global_load_dwordx2 v[30:31], v[30:31], off nt
	s_nop 0
	global_load_dwordx2 v[32:33], v[32:33], off nt
	s_nop 0
	global_load_dwordx2 v[34:35], v[34:35], off nt
	s_nop 0
	global_load_dwordx2 v[2:3], v[6:7], off nt
	s_nop 0
	global_load_dwordx2 v[6:7], v[8:9], off nt
	s_nop 0
	global_load_dwordx2 v[8:9], v[10:11], off nt
	s_nop 0
	global_load_dwordx2 v[10:11], v[12:13], off nt
	s_addc_u32 s1, s5, s16
	v_lshl_add_u64 v[12:13], s[0:1], 0, v[0:1]
	v_add_co_u32_e32 v36, vcc, s31, v12
	s_lshl_b64 s[16:17], s[18:19], 12
	s_nop 0
	v_addc_co_u32_e32 v37, vcc, 0, v13, vcc
	v_add_co_u32_e32 v12, vcc, s34, v12
	s_add_u32 s0, s8, s16
	s_nop 0
	v_addc_co_u32_e32 v13, vcc, 0, v13, vcc
	global_load_dwordx2 v[12:13], v[12:13], off offset:1024
	s_nop 0
	global_load_dwordx2 v[36:37], v[36:37], off offset:1024
	s_addc_u32 s1, s9, s17
	s_add_i32 s35, s35, s88
	s_add_i32 s2, s2, s10
	s_cmpk_lt_i32 s35, 0x600
	s_waitcnt vmcnt(17)
	v_lshlrev_b32_e32 v38, 16, v4
	v_and_b32_e32 v39, 0xffff0000, v4
	v_lshlrev_b32_e32 v4, 16, v5
	v_and_b32_e32 v5, 0xffff0000, v5
	v_pk_add_f32 v[38:39], v[38:39], 0 op_sel_hi:[1,0]
	v_pk_add_f32 v[4:5], v[4:5], 0 op_sel_hi:[1,0]
	s_waitcnt vmcnt(16)
	v_lshlrev_b32_e32 v40, 16, v14
	v_and_b32_e32 v41, 0xffff0000, v14
	v_lshlrev_b32_e32 v14, 16, v15
	v_and_b32_e32 v15, 0xffff0000, v15
	s_waitcnt vmcnt(15)
	v_lshlrev_b32_e32 v42, 16, v16
	v_and_b32_e32 v43, 0xffff0000, v16
	v_lshlrev_b32_e32 v16, 16, v17
	v_and_b32_e32 v17, 0xffff0000, v17
	s_waitcnt vmcnt(5)
; __device__ __forceinline__ float bf_lo(unsigned w) { return __uint_as_float(w << 16); }
; __device__ __forceinline__ float bf_hi(unsigned w) { return __uint_as_float(w & 0xffff0000u); }
; __device__ __forceinline__ unsigned pk2(float lo, float hi) { return pg8::cvt_pk_bf16(lo, hi); }
; __device__ __forceinline__ void fix_gate(const float* part, int nsl, const bf16_t* z, bf16_t* mixed, int gw, int ngw, int lane) {
;     ...
; #pragma unroll 8
;         for (int s = 0; s < nsl; ++s) { const u32x2_t wa = __builtin_nontemporal_load((const u32x2_t*)(p + (size_t)s * (256 * 2048))), wb = __builtin_nontemporal_load((const u32x2_t*)(p + (size_t)(s + nsl) * (256 * 2048)));
;             a += (f32x4_t){bf_lo(wa.x), bf_hi(wa.x), bf_lo(wa.y), bf_hi(wa.y)}; b += (f32x4_t){bf_lo(wb.x), bf_hi(wb.x), bf_lo(wb.y), bf_hi(wb.y)}; }
;         const u32x2_t gc = *(const u32x2_t*)(z + (size_t)row * DIN + ZO_GC + col), ga = *(const u32x2_t*)(z + (size_t)row * DIN + ZO_GA + col);
;         u32x2_t w;
;         w.x = pk2(bf_lo(gc.x) * a.x + bf_lo(ga.x) * b.x, bf_hi(gc.x) * a.y + bf_hi(ga.x) * b.y);
;         w.y = pk2(bf_lo(gc.y) * a.z + bf_lo(ga.y) * b.z, bf_hi(gc.y) * a.w + bf_hi(ga.y) * b.w);
;         *(u32x2_t*)(mixed + (size_t)row * DM + col) = w;
	v_lshlrev_b32_e32 v62, 16, v2
	v_and_b32_e32 v63, 0xffff0000, v2
	v_lshlrev_b32_e32 v2, 16, v3
	v_and_b32_e32 v3, 0xffff0000, v3
	s_waitcnt vmcnt(4)
	v_lshlrev_b32_e32 v64, 16, v6
	v_and_b32_e32 v65, 0xffff0000, v6
	v_lshlrev_b32_e32 v6, 16, v7
	v_and_b32_e32 v7, 0xffff0000, v7
	s_waitcnt vmcnt(3)
	v_lshlrev_b32_e32 v66, 16, v8
	v_and_b32_e32 v67, 0xffff0000, v8
	v_lshlrev_b32_e32 v8, 16, v9
	v_and_b32_e32 v9, 0xffff0000, v9
	v_pk_add_f32 v[62:63], v[62:63], 0 op_sel_hi:[1,0]
	v_pk_add_f32 v[2:3], v[2:3], 0 op_sel_hi:[1,0]
	s_waitcnt vmcnt(2)
	v_lshlrev_b32_e32 v68, 16, v10
	v_and_b32_e32 v69, 0xffff0000, v10
	v_lshlrev_b32_e32 v10, 16, v11
	v_and_b32_e32 v11, 0xffff0000, v11
	v_pk_add_f32 v[4:5], v[4:5], v[6:7]
	v_pk_add_f32 v[6:7], v[38:39], v[64:65]
	v_pk_add_f32 v[2:3], v[2:3], v[8:9]
	v_pk_add_f32 v[8:9], v[62:63], v[66:67]
	v_lshlrev_b32_e32 v44, 16, v18
	v_and_b32_e32 v45, 0xffff0000, v18
	v_lshlrev_b32_e32 v18, 16, v19
	v_and_b32_e32 v19, 0xffff0000, v19
	v_pk_add_f32 v[6:7], v[6:7], v[68:69]
	v_pk_add_f32 v[4:5], v[4:5], v[10:11]
	v_pk_add_f32 v[8:9], v[8:9], v[40:41]
	v_pk_add_f32 v[2:3], v[2:3], v[14:15]
	v_lshlrev_b32_e32 v46, 16, v20
	v_and_b32_e32 v47, 0xffff0000, v20
	v_lshlrev_b32_e32 v20, 16, v21
	v_and_b32_e32 v21, 0xffff0000, v21
	v_lshlrev_b32_e32 v48, 16, v22
	v_and_b32_e32 v49, 0xffff0000, v22
	v_lshlrev_b32_e32 v22, 16, v23
	v_and_b32_e32 v23, 0xffff0000, v23
	v_pk_add_f32 v[4:5], v[4:5], v[16:17]
	v_pk_add_f32 v[6:7], v[6:7], v[42:43]
	v_pk_add_f32 v[2:3], v[2:3], v[18:19]
	v_pk_add_f32 v[8:9], v[8:9], v[44:45]
	v_lshlrev_b32_e32 v50, 16, v24
	v_and_b32_e32 v51, 0xffff0000, v24
	v_lshlrev_b32_e32 v24, 16, v25
	v_and_b32_e32 v25, 0xffff0000, v25
	v_lshlrev_b32_e32 v52, 16, v26
	v_and_b32_e32 v53, 0xffff0000, v26
	v_lshlrev_b32_e32 v26, 16, v27
	v_and_b32_e32 v27, 0xffff0000, v27
	v_pk_add_f32 v[6:7], v[6:7], v[46:47]
	v_pk_add_f32 v[4:5], v[4:5], v[20:21]
	v_pk_add_f32 v[8:9], v[8:9], v[48:49]
	v_pk_add_f32 v[2:3], v[2:3], v[22:23]
	v_lshlrev_b32_e32 v54, 16, v28
	v_and_b32_e32 v55, 0xffff0000, v28
	v_lshlrev_b32_e32 v28, 16, v29
	v_and_b32_e32 v29, 0xffff0000, v29
	v_lshlrev_b32_e32 v56, 16, v30
	v_and_b32_e32 v57, 0xffff0000, v30
	v_lshlrev_b32_e32 v30, 16, v31
	v_and_b32_e32 v31, 0xffff0000, v31
	v_pk_add_f32 v[4:5], v[4:5], v[24:25]
	v_pk_add_f32 v[6:7], v[6:7], v[50:51]
	v_pk_add_f32 v[2:3], v[2:3], v[26:27]
	v_pk_add_f32 v[8:9], v[8:9], v[52:53]
	v_lshlrev_b32_e32 v58, 16, v32
	v_and_b32_e32 v59, 0xffff0000, v32
	v_lshlrev_b32_e32 v32, 16, v33
	v_and_b32_e32 v33, 0xffff0000, v33
	v_lshlrev_b32_e32 v60, 16, v34
	v_and_b32_e32 v61, 0xffff0000, v34
	v_lshlrev_b32_e32 v34, 16, v35
	v_and_b32_e32 v35, 0xffff0000, v35
	v_pk_add_f32 v[6:7], v[6:7], v[54:55]
	v_pk_add_f32 v[4:5], v[4:5], v[28:29]
	v_pk_add_f32 v[8:9], v[8:9], v[56:57]
	v_pk_add_f32 v[2:3], v[2:3], v[30:31]
	v_pk_add_f32 v[4:5], v[4:5], v[32:33]
	v_pk_add_f32 v[6:7], v[6:7], v[58:59]
	v_pk_add_f32 v[2:3], v[2:3], v[34:35]
	v_pk_add_f32 v[8:9], v[8:9], v[60:61]
	s_waitcnt vmcnt(1)
	v_lshlrev_b32_e32 v11, 16, v12
	v_and_b32_e32 v39, 0xffff0000, v12
	v_lshlrev_b32_e32 v63, 16, v13
	v_and_b32_e32 v13, 0xffff0000, v13
	s_waitcnt vmcnt(0)
	v_and_b32_e32 v12, 0xffff0000, v37
	v_mov_b32_e32 v15, v8
	v_mov_b32_e32 v8, v7
	v_mov_b32_e32 v7, v2
	v_mov_b32_e32 v2, v5
	v_lshlrev_b32_e32 v10, 16, v36
	v_and_b32_e32 v38, 0xffff0000, v36
	v_lshlrev_b32_e32 v62, 16, v37
	v_mov_b32_e32 v14, v6
	v_mov_b32_e32 v6, v4
	v_pk_mul_f32 v[2:3], v[2:3], v[12:13]
	v_pk_mul_f32 v[4:5], v[14:15], v[10:11]
	v_pk_mul_f32 v[8:9], v[8:9], v[38:39]
	v_pk_mul_f32 v[6:7], v[6:7], v[62:63]
	v_add_f32_e32 v3, v2, v3
	v_add_f32_e32 v4, v4, v5
	v_add_f32_e32 v5, v8, v9
	v_add_f32_e32 v6, v6, v7
	v_cvt_pk_bf16_f32 v2, v4, v5
	v_cvt_pk_bf16_f32 v3, v6, v3
	global_store_dwordx2 v0, v[2:3], s[0:1]
	s_cbranch_scc1 .LBB0_1040

; __device__ __forceinline__ float bf_lo(unsigned w) { return __uint_as_float(w << 16); }
; __device__ __forceinline__ float bf_hi(unsigned w) { return __uint_as_float(w & 0xffff0000u); }
; template <int MODE> __device__ __forceinline__ void fix_resid(const float* part, int nsl, const float* xp, const float* xs, const float* meta, float* xbuf, bf16_t* xb, float* ss, float* out, int gw, int ngw, int lane) {
;     for (int it = gw; it < NTAIL * 8; it += ngw) {
;         const int rloc = it >> 3, row = TAIL0 + rloc, col = (it & 7) * 256 + lane * 4;
;         const bf16_t* p = (const bf16_t*)part + (size_t)rloc * 2048 + col;
;         f32x4_t v = (f32x4_t){0.f, 0.f, 0.f, 0.f};
; #pragma unroll 8
;         for (int s = 0; s < nsl; ++s) { const u32x2_t w = __builtin_nontemporal_load((const u32x2_t*)(p + (size_t)s * (256 * 2048))); v += (f32x4_t){bf_lo(w.x), bf_hi(w.x), bf_lo(w.y), bf_hi(w.y)}; }
;         const float scale = (MODE == 1) ? 1.0f : 0.5f;
;         const u32x2_t bw = *(const u32x2_t*)(xb + (size_t)row * DM + col);
;         const f32x4_t o = (f32x4_t){bf_lo(bw.x), bf_hi(bw.x), bf_lo(bw.y), bf_hi(bw.y)} + v * scale;
.LBB0_1555:
	s_ashr_i32 s2, s83, 3
	s_lshl_b32 s0, s10, 1
	s_ashr_i32 s3, s2, 31
	s_and_b32 s0, s0, 0xe00
	s_lshl_b64 s[4:5], s[2:3], 12
	s_add_u32 s4, s90, s4
	v_lshl_or_b32 v0, v241, 1, s0
	s_addc_u32 s5, s91, s5
	s_waitcnt vmcnt(0)
	s_add_u32 s6, s4, 0x2b40000
	s_addc_u32 s7, s5, 0
	v_mov_b32_e32 v2, 0
	v_mov_b32_e32 v3, v1
	v_mov_b32_e32 v4, 0
	v_mov_b32_e32 v5, v1
	global_load_dwordx2 v[32:33], v0, s[6:7] nt
	s_add_u32 s6, s6, 0x100000
	s_addc_u32 s7, s7, 0
	global_load_dwordx2 v[34:35], v0, s[6:7] nt
	s_add_u32 s6, s6, 0x100000
	s_addc_u32 s7, s7, 0
	global_load_dwordx2 v[36:37], v0, s[6:7] nt
	s_add_u32 s6, s6, 0x100000
	s_addc_u32 s7, s7, 0
	global_load_dwordx2 v[38:39], v0, s[6:7] nt
	s_add_u32 s6, s6, 0x100000
	s_addc_u32 s7, s7, 0
	global_load_dwordx2 v[40:41], v0, s[6:7] nt
	s_add_u32 s6, s6, 0x100000
	s_addc_u32 s7, s7, 0
	global_load_dwordx2 v[42:43], v0, s[6:7] nt
	s_add_u32 s6, s6, 0x100000
	s_addc_u32 s7, s7, 0
	global_load_dwordx2 v[44:45], v0, s[6:7] nt
	s_add_u32 s6, s6, 0x100000
	s_addc_u32 s7, s7, 0
	global_load_dwordx2 v[46:47], v0, s[6:7] nt
	s_add_u32 s6, s6, 0x100000
	s_addc_u32 s7, s7, 0
	global_load_dwordx2 v[48:49], v0, s[6:7] nt
	s_add_u32 s6, s6, 0x100000
	s_addc_u32 s7, s7, 0
	global_load_dwordx2 v[50:51], v0, s[6:7] nt
	s_add_u32 s6, s6, 0x100000
	s_addc_u32 s7, s7, 0
	global_load_dwordx2 v[52:53], v0, s[6:7] nt
	s_add_u32 s6, s6, 0x100000
	s_addc_u32 s7, s7, 0
	global_load_dwordx2 v[54:55], v0, s[6:7] nt
	s_add_u32 s6, s6, 0x100000
	s_addc_u32 s7, s7, 0
	global_load_dwordx2 v[56:57], v0, s[6:7] nt
	s_add_u32 s6, s6, 0x100000
	s_addc_u32 s7, s7, 0
	global_load_dwordx2 v[58:59], v0, s[6:7] nt
	s_add_u32 s6, s6, 0x100000
	s_addc_u32 s7, s7, 0
	global_load_dwordx2 v[60:61], v0, s[6:7] nt
	s_add_u32 s6, s6, 0x100000
	s_addc_u32 s7, s7, 0
	global_load_dwordx2 v[62:63], v0, s[6:7] nt
	s_add_u32 s6, s6, 0x100000
	s_addc_u32 s7, s7, 0
	global_load_dwordx2 v[64:65], v0, s[6:7] nt
	s_add_u32 s6, s6, 0x100000
	s_addc_u32 s7, s7, 0
	global_load_dwordx2 v[66:67], v0, s[6:7] nt
	s_add_u32 s6, s6, 0x100000
	s_addc_u32 s7, s7, 0
	global_load_dwordx2 v[68:69], v0, s[6:7] nt
	s_add_u32 s6, s6, 0x100000
	s_addc_u32 s7, s7, 0
	global_load_dwordx2 v[70:71], v0, s[6:7] nt
	s_add_u32 s6, s6, 0x100000
	s_addc_u32 s7, s7, 0
	global_load_dwordx2 v[72:73], v0, s[6:7] nt
	s_add_u32 s6, s6, 0x100000
	s_addc_u32 s7, s7, 0
	global_load_dwordx2 v[74:75], v0, s[6:7] nt
	s_add_u32 s6, s6, 0x100000
	s_addc_u32 s7, s7, 0
	global_load_dwordx2 v[76:77], v0, s[6:7] nt
	s_add_u32 s6, s6, 0x100000
	s_addc_u32 s7, s7, 0
	global_load_dwordx2 v[78:79], v0, s[6:7] nt
	s_add_u32 s6, s6, 0x100000
	s_addc_u32 s7, s7, 0
	global_load_dwordx2 v[80:81], v0, s[6:7] nt
	s_add_u32 s6, s6, 0x100000
	s_addc_u32 s7, s7, 0
	global_load_dwordx2 v[82:83], v0, s[6:7] nt
	s_add_u32 s6, s6, 0x100000
	s_addc_u32 s7, s7, 0
	global_load_dwordx2 v[84:85], v0, s[6:7] nt
	s_add_u32 s6, s6, 0x100000
	s_addc_u32 s7, s7, 0
	global_load_dwordx2 v[86:87], v0, s[6:7] nt
	s_add_u32 s6, s6, 0x100000
	s_addc_u32 s7, s7, 0
	global_load_dwordx2 v[88:89], v0, s[6:7] nt
	s_add_u32 s6, s6, 0x100000
	s_addc_u32 s7, s7, 0
	global_load_dwordx2 v[90:91], v0, s[6:7] nt
	s_add_u32 s6, s6, 0x100000
	s_addc_u32 s7, s7, 0
	global_load_dwordx2 v[92:93], v0, s[6:7] nt
	s_add_u32 s6, s6, 0x100000
	s_addc_u32 s7, s7, 0
	global_load_dwordx2 v[94:95], v0, s[6:7] nt
	s_add_i32 s6, s2, 0x2000
	s_lshl_b32 s0, s83, 8
	s_ashr_i32 s7, s6, 31
	s_and_b32 s0, s0, 0x700
	s_lshl_b64 s[4:5], s[6:7], 12
	v_or_b32_e32 v0, s0, v241
	s_add_u32 s4, s96, s4
	s_addc_u32 s5, s97, s5
	v_lshlrev_b32_e32 v6, 1, v0
	global_load_dwordx2 v[6:7], v6, s[4:5]
	s_waitcnt vmcnt(25)
	v_lshlrev_b32_e32 v24, 16, v32
	v_and_b32_e32 v25, 0xffff0000, v32
	v_lshlrev_b32_e32 v10, 16, v33
	v_and_b32_e32 v11, 0xffff0000, v33
	v_pk_add_f32 v[2:3], v[2:3], v[24:25]
	v_pk_add_f32 v[4:5], v[4:5], v[10:11]
	v_lshlrev_b32_e32 v24, 16, v34
	v_and_b32_e32 v25, 0xffff0000, v34
	v_lshlrev_b32_e32 v10, 16, v35
	v_and_b32_e32 v11, 0xffff0000, v35
	v_pk_add_f32 v[2:3], v[2:3], v[24:25]
	v_pk_add_f32 v[4:5], v[4:5], v[10:11]
	v_lshlrev_b32_e32 v24, 16, v36
	v_and_b32_e32 v25, 0xffff0000, v36
	v_lshlrev_b32_e32 v10, 16, v37
	v_and_b32_e32 v11, 0xffff0000, v37
	v_pk_add_f32 v[2:3], v[2:3], v[24:25]
	v_pk_add_f32 v[4:5], v[4:5], v[10:11]
	v_lshlrev_b32_e32 v24, 16, v38
	v_and_b32_e32 v25, 0xffff0000, v38
	v_lshlrev_b32_e32 v10, 16, v39
	v_and_b32_e32 v11, 0xffff0000, v39
	v_pk_add_f32 v[2:3], v[2:3], v[24:25]
	v_pk_add_f32 v[4:5], v[4:5], v[10:11]
	v_lshlrev_b32_e32 v24, 16, v40
	v_and_b32_e32 v25, 0xffff0000, v40
	v_lshlrev_b32_e32 v10, 16, v41
	v_and_b32_e32 v11, 0xffff0000, v41
	v_pk_add_f32 v[2:3], v[2:3], v[24:25]
	v_pk_add_f32 v[4:5], v[4:5], v[10:11]
	v_lshlrev_b32_e32 v24, 16, v42
	v_and_b32_e32 v25, 0xffff0000, v42
	v_lshlrev_b32_e32 v10, 16, v43
	v_and_b32_e32 v11, 0xffff0000, v43
	v_pk_add_f32 v[2:3], v[2:3], v[24:25]
	v_pk_add_f32 v[4:5], v[4:5], v[10:11]
	v_lshlrev_b32_e32 v24, 16, v44
	v_and_b32_e32 v25, 0xffff0000, v44
	v_lshlrev_b32_e32 v10, 16, v45
	v_and_b32_e32 v11, 0xffff0000, v45
	v_pk_add_f32 v[2:3], v[2:3], v[24:25]
	v_pk_add_f32 v[4:5], v[4:5], v[10:11]
	v_lshlrev_b32_e32 v24, 16, v46
	v_and_b32_e32 v25, 0xffff0000, v46
	v_lshlrev_b32_e32 v10, 16, v47
	v_and_b32_e32 v11, 0xffff0000, v47
	v_pk_add_f32 v[2:3], v[2:3], v[24:25]
	v_pk_add_f32 v[4:5], v[4:5], v[10:11]
	s_waitcnt vmcnt(17)
; __device__ __forceinline__ float bf_lo(unsigned w) { return __uint_as_float(w << 16); }
; __device__ __forceinline__ float bf_hi(unsigned w) { return __uint_as_float(w & 0xffff0000u); }
; template <int MODE> __device__ __forceinline__ void fix_resid(const float* part, int nsl, const float* xp, const float* xs, const float* meta, float* xbuf, bf16_t* xb, float* ss, float* out, int gw, int ngw, int lane) {
;     ...
;         for (int s = 0; s < nsl; ++s) { const u32x2_t w = __builtin_nontemporal_load((const u32x2_t*)(p + (size_t)s * (256 * 2048))); v += (f32x4_t){bf_lo(w.x), bf_hi(w.x), bf_lo(w.y), bf_hi(w.y)}; }
;         const float scale = (MODE == 1) ? 1.0f : 0.5f;
;         const u32x2_t bw = *(const u32x2_t*)(xb + (size_t)row * DM + col);
;         const f32x4_t o = (f32x4_t){bf_lo(bw.x), bf_hi(bw.x), bf_lo(bw.y), bf_hi(bw.y)} + v * scale;
;         if (MODE == 2) { float* dst = y_row(out, row); if (dst) __builtin_nontemporal_store(o, (f32x4_t*)(dst + col)); }
	v_lshlrev_b32_e32 v24, 16, v48
	v_and_b32_e32 v25, 0xffff0000, v48
	v_lshlrev_b32_e32 v10, 16, v49
	v_and_b32_e32 v11, 0xffff0000, v49
	v_pk_add_f32 v[2:3], v[2:3], v[24:25]
	v_pk_add_f32 v[4:5], v[4:5], v[10:11]
	v_lshlrev_b32_e32 v24, 16, v50
	v_and_b32_e32 v25, 0xffff0000, v50
	v_lshlrev_b32_e32 v10, 16, v51
	v_and_b32_e32 v11, 0xffff0000, v51
	v_pk_add_f32 v[2:3], v[2:3], v[24:25]
	v_pk_add_f32 v[4:5], v[4:5], v[10:11]
	v_lshlrev_b32_e32 v24, 16, v52
	v_and_b32_e32 v25, 0xffff0000, v52
	v_lshlrev_b32_e32 v10, 16, v53
	v_and_b32_e32 v11, 0xffff0000, v53
	v_pk_add_f32 v[2:3], v[2:3], v[24:25]
	v_pk_add_f32 v[4:5], v[4:5], v[10:11]
	v_lshlrev_b32_e32 v24, 16, v54
	v_and_b32_e32 v25, 0xffff0000, v54
	v_lshlrev_b32_e32 v10, 16, v55
	v_and_b32_e32 v11, 0xffff0000, v55
	v_pk_add_f32 v[2:3], v[2:3], v[24:25]
	v_pk_add_f32 v[4:5], v[4:5], v[10:11]
	v_lshlrev_b32_e32 v24, 16, v56
	v_and_b32_e32 v25, 0xffff0000, v56
	v_lshlrev_b32_e32 v10, 16, v57
	v_and_b32_e32 v11, 0xffff0000, v57
	v_pk_add_f32 v[2:3], v[2:3], v[24:25]
	v_pk_add_f32 v[4:5], v[4:5], v[10:11]
	v_lshlrev_b32_e32 v24, 16, v58
	v_and_b32_e32 v25, 0xffff0000, v58
	v_lshlrev_b32_e32 v10, 16, v59
	v_and_b32_e32 v11, 0xffff0000, v59
	v_pk_add_f32 v[2:3], v[2:3], v[24:25]
	v_pk_add_f32 v[4:5], v[4:5], v[10:11]
	v_lshlrev_b32_e32 v24, 16, v60
	v_and_b32_e32 v25, 0xffff0000, v60
	v_lshlrev_b32_e32 v10, 16, v61
	v_and_b32_e32 v11, 0xffff0000, v61
	v_pk_add_f32 v[2:3], v[2:3], v[24:25]
	v_pk_add_f32 v[4:5], v[4:5], v[10:11]
	v_lshlrev_b32_e32 v24, 16, v62
	v_and_b32_e32 v25, 0xffff0000, v62
	v_lshlrev_b32_e32 v10, 16, v63
	v_and_b32_e32 v11, 0xffff0000, v63
	v_pk_add_f32 v[2:3], v[2:3], v[24:25]
	v_pk_add_f32 v[4:5], v[4:5], v[10:11]
	s_waitcnt vmcnt(9)
	v_lshlrev_b32_e32 v24, 16, v64
	v_and_b32_e32 v25, 0xffff0000, v64
	v_lshlrev_b32_e32 v10, 16, v65
	v_and_b32_e32 v11, 0xffff0000, v65
	v_pk_add_f32 v[2:3], v[2:3], v[24:25]
	v_pk_add_f32 v[4:5], v[4:5], v[10:11]
	v_lshlrev_b32_e32 v24, 16, v66
	v_and_b32_e32 v25, 0xffff0000, v66
	v_lshlrev_b32_e32 v10, 16, v67
	v_and_b32_e32 v11, 0xffff0000, v67
	v_pk_add_f32 v[2:3], v[2:3], v[24:25]
	v_pk_add_f32 v[4:5], v[4:5], v[10:11]
	v_lshlrev_b32_e32 v24, 16, v68
	v_and_b32_e32 v25, 0xffff0000, v68
	v_lshlrev_b32_e32 v10, 16, v69
	v_and_b32_e32 v11, 0xffff0000, v69
	v_pk_add_f32 v[2:3], v[2:3], v[24:25]
	v_pk_add_f32 v[4:5], v[4:5], v[10:11]
	v_lshlrev_b32_e32 v24, 16, v70
	v_and_b32_e32 v25, 0xffff0000, v70
	v_lshlrev_b32_e32 v10, 16, v71
	v_and_b32_e32 v11, 0xffff0000, v71
	v_pk_add_f32 v[2:3], v[2:3], v[24:25]
	v_pk_add_f32 v[4:5], v[4:5], v[10:11]
	v_lshlrev_b32_e32 v24, 16, v72
	v_and_b32_e32 v25, 0xffff0000, v72
	v_lshlrev_b32_e32 v10, 16, v73
	v_and_b32_e32 v11, 0xffff0000, v73
	v_pk_add_f32 v[2:3], v[2:3], v[24:25]
	v_pk_add_f32 v[4:5], v[4:5], v[10:11]
	v_lshlrev_b32_e32 v24, 16, v74
	v_and_b32_e32 v25, 0xffff0000, v74
	v_lshlrev_b32_e32 v10, 16, v75
	v_and_b32_e32 v11, 0xffff0000, v75
	v_pk_add_f32 v[2:3], v[2:3], v[24:25]
	v_pk_add_f32 v[4:5], v[4:5], v[10:11]
	v_lshlrev_b32_e32 v24, 16, v76
	v_and_b32_e32 v25, 0xffff0000, v76
	v_lshlrev_b32_e32 v10, 16, v77
	v_and_b32_e32 v11, 0xffff0000, v77
	v_pk_add_f32 v[2:3], v[2:3], v[24:25]
	v_pk_add_f32 v[4:5], v[4:5], v[10:11]
	v_lshlrev_b32_e32 v24, 16, v78
	v_and_b32_e32 v25, 0xffff0000, v78
	v_lshlrev_b32_e32 v10, 16, v79
	v_and_b32_e32 v11, 0xffff0000, v79
	v_pk_add_f32 v[2:3], v[2:3], v[24:25]
	v_pk_add_f32 v[4:5], v[4:5], v[10:11]
	s_waitcnt vmcnt(1)
	v_lshlrev_b32_e32 v24, 16, v80
	v_and_b32_e32 v25, 0xffff0000, v80
	v_lshlrev_b32_e32 v10, 16, v81
	v_and_b32_e32 v11, 0xffff0000, v81
	v_pk_add_f32 v[2:3], v[2:3], v[24:25]
	v_pk_add_f32 v[4:5], v[4:5], v[10:11]
	v_lshlrev_b32_e32 v24, 16, v82
	v_and_b32_e32 v25, 0xffff0000, v82
	v_lshlrev_b32_e32 v10, 16, v83
	v_and_b32_e32 v11, 0xffff0000, v83
	v_pk_add_f32 v[2:3], v[2:3], v[24:25]
	v_pk_add_f32 v[4:5], v[4:5], v[10:11]
	v_lshlrev_b32_e32 v24, 16, v84
	v_and_b32_e32 v25, 0xffff0000, v84
	v_lshlrev_b32_e32 v10, 16, v85
	v_and_b32_e32 v11, 0xffff0000, v85
	v_pk_add_f32 v[2:3], v[2:3], v[24:25]
	v_pk_add_f32 v[4:5], v[4:5], v[10:11]
	v_lshlrev_b32_e32 v24, 16, v86
	v_and_b32_e32 v25, 0xffff0000, v86
	v_lshlrev_b32_e32 v10, 16, v87
	v_and_b32_e32 v11, 0xffff0000, v87
	v_pk_add_f32 v[2:3], v[2:3], v[24:25]
	v_pk_add_f32 v[4:5], v[4:5], v[10:11]
	v_lshlrev_b32_e32 v24, 16, v88
	v_and_b32_e32 v25, 0xffff0000, v88
	v_lshlrev_b32_e32 v10, 16, v89
	v_and_b32_e32 v11, 0xffff0000, v89
	v_pk_add_f32 v[2:3], v[2:3], v[24:25]
	v_pk_add_f32 v[4:5], v[4:5], v[10:11]
	v_lshlrev_b32_e32 v24, 16, v90
	v_and_b32_e32 v25, 0xffff0000, v90
	v_lshlrev_b32_e32 v10, 16, v91
	v_and_b32_e32 v11, 0xffff0000, v91
	v_pk_add_f32 v[2:3], v[2:3], v[24:25]
	v_pk_add_f32 v[4:5], v[4:5], v[10:11]
	v_lshlrev_b32_e32 v24, 16, v92
	v_and_b32_e32 v25, 0xffff0000, v92
	v_lshlrev_b32_e32 v10, 16, v93
	v_and_b32_e32 v11, 0xffff0000, v93
	v_pk_add_f32 v[2:3], v[2:3], v[24:25]
	v_pk_add_f32 v[4:5], v[4:5], v[10:11]
	v_lshlrev_b32_e32 v24, 16, v94
	v_and_b32_e32 v25, 0xffff0000, v94
	v_lshlrev_b32_e32 v10, 16, v95
	v_and_b32_e32 v11, 0xffff0000, v95
	v_pk_add_f32 v[2:3], v[2:3], v[24:25]
	v_pk_add_f32 v[4:5], v[4:5], v[10:11]
	s_cmp_lt_i32 s2, 64
	s_mov_b64 s[12:13], -1
	s_cbranch_scc1 .LBB0_1560
	s_andn2_b64 vcc, exec, s[12:13]
	s_cbranch_vccz .LBB0_1561
